# v45 + loop-top scalar bookkeeping and buffer-rotation VALU moved into the MFMA shadows of slot 0 (loop starts directly with the QK MFMA)
# speedup vs baseline: 1.0520x; 1.0109x over previous
.Latt_loop:
	s_waitcnt lgkmcnt(5)
	v_mfma_f32_32x32x16_bf16 v[98:113], v[238:241], v[134:137], 0
	v_exp_f32_e32 v66, v66
	v_exp_f32_e32 v67, v67
	v_exp_f32_e32 v68, v68
	s_add_i32 s13, s12, 1
	s_cmp_eq_u32 s12, 2
	s_cselect_b32 s12, 0, s13
	s_mul_i32 s15, s12, 0x4800
	s_mul_i32 s16, s12, 0x6000
	s_add_i32 s16, s16, 0xd800
	s_add_i32 s17, s14, 2
	s_min_u32 s17, s17, s11
	s_lshl_b32 s64, s17, 17
	s_add_u32 s18, s64, s83
	s_mov_b32 s19, 0
	s_add_i32 s14, s14, 1
	v_mfma_f32_32x32x16_bf16 v[34:49], v[182:185], v[118:121], v[34:49]
	v_exp_f32_e32 v69, v69
	v_exp_f32_e32 v70, v70
	v_exp_f32_e32 v71, v71
	v_mov_b32_e32 v250, v251
	v_add3_u32 v251, s15, v236, v210
	v_mov_b32_e32 v252, v215
	v_add_u32_e32 v215, s16, v232
	ds_read_b128 v[238:241], v250 offset:4672
	ds_read_b64_tr_b16 v[182:183], v252 offset:3072
	ds_read_b64_tr_b16 v[184:185], v252 offset:4608
	v_mfma_f32_32x32x16_bf16 v[50:65], v[186:189], v[118:121], v[50:65]
	v_exp_f32_e32 v72, v72
	v_exp_f32_e32 v73, v73
	v_cvt_pk_bf16_f32 v66, v66, v67
	v_cvt_pk_bf16_f32 v67, v68, v69
	ds_read_b64_tr_b16 v[186:187], v252 offset:3136
	ds_read_b64_tr_b16 v[188:189], v252 offset:4672
	v_mfma_f32_16x16x32_bf16 v[170:173], v[130:133], v[118:121], v[170:173]
	v_cvt_pk_bf16_f32 v68, v70, v71
	v_cvt_pk_bf16_f32 v69, v72, v73
	s_waitcnt lgkmcnt(5)
	v_mfma_f32_32x32x16_bf16 v[98:113], v[242:245], v[138:141], v[98:113]
	v_exp_f32_e32 v82, v82
	v_exp_f32_e32 v83, v83
	v_exp_f32_e32 v84, v84
	ds_read_b128 v[242:245], v250 offset:4704
	s_waitcnt vmcnt(0)
	v_add_u32_e32 v246, s15, v204
	v_add_u32_e32 v247, s16, v231
	ds_write_b128 v246, v[158:161]
	ds_write_b128 v246, v[162:165] offset:9216
	v_mfma_f32_32x32x16_bf16 v[2:17], v[174:177], v[66:69], v[2:17]
	v_exp_f32_e32 v85, v85
	v_exp_f32_e32 v86, v86
	v_exp_f32_e32 v87, v87
	ds_write_b128 v247, v[150:153]
	ds_write_b128 v247, v[154:157] offset:12288
	v_mfma_f32_32x32x16_bf16 v[18:33], v[178:181], v[66:69], v[18:33]
	v_exp_f32_e32 v88, v88
	v_exp_f32_e32 v89, v89
	v_cvt_pk_bf16_f32 v82, v82, v83
	v_cvt_pk_bf16_f32 v83, v84, v85
	s_add_u32 s18, s100, s64
	s_addc_u32 s19, s101, 0
	global_load_dwordx4 v[158:161], v248, s[18:19]
	global_load_dwordx4 v[162:165], v249, s[18:19]
	v_mfma_f32_16x16x32_bf16 v[166:169], v[130:133], v[66:69], v[166:169]
	v_cvt_pk_bf16_f32 v84, v86, v87
	v_cvt_pk_bf16_f32 v85, v88, v89
	s_waitcnt lgkmcnt(9)
	v_mfma_f32_32x32x16_bf16 v[114:129], v[238:241], v[142:145], 0
	v_exp_f32_e32 v74, v74
	v_exp_f32_e32 v75, v75
	v_exp_f32_e32 v76, v76
	ds_read_b128 v[238:241], v250 offset:9216
	v_mfma_f32_32x32x16_bf16 v[34:49], v[174:177], v[82:85], v[34:49]
	v_exp_f32_e32 v77, v77
	v_exp_f32_e32 v78, v78
	v_exp_f32_e32 v79, v79
	ds_read_b64_tr_b16 v[174:175], v252 offset:6144
	ds_read_b64_tr_b16 v[176:177], v252 offset:7680
	v_mfma_f32_32x32x16_bf16 v[50:65], v[178:181], v[82:85], v[50:65]
	v_exp_f32_e32 v80, v80
	v_exp_f32_e32 v81, v81
	v_cvt_pk_bf16_f32 v70, v74, v75
	v_cvt_pk_bf16_f32 v71, v76, v77
	ds_read_b64_tr_b16 v[178:179], v252 offset:6208
	ds_read_b64_tr_b16 v[180:181], v252 offset:7744
	v_mfma_f32_16x16x32_bf16 v[170:173], v[130:133], v[82:85], v[170:173]
	v_cvt_pk_bf16_f32 v72, v78, v79
	v_cvt_pk_bf16_f32 v73, v80, v81
	s_waitcnt lgkmcnt(9)
	v_mfma_f32_32x32x16_bf16 v[114:129], v[242:245], v[146:149], v[114:129]
	v_exp_f32_e32 v90, v90
	v_exp_f32_e32 v91, v91
	v_exp_f32_e32 v92, v92
	ds_read_b128 v[242:245], v250 offset:9248
	v_mfma_f32_32x32x16_bf16 v[2:17], v[182:185], v[70:73], v[2:17]
	v_exp_f32_e32 v93, v93
	v_exp_f32_e32 v94, v94
	v_exp_f32_e32 v95, v95
	s_add_u32 s18, s18, 0x1040000
	s_addc_u32 s19, s19, 0
	global_load_dwordx4 v[150:153], v248, s[18:19]
	global_load_dwordx4 v[154:157], v249, s[18:19]
	v_mfma_f32_32x32x16_bf16 v[18:33], v[186:189], v[70:73], v[18:33]
	v_exp_f32_e32 v96, v96
	v_exp_f32_e32 v97, v97
	v_cvt_pk_bf16_f32 v86, v90, v91
	v_cvt_pk_bf16_f32 v87, v92, v93
	v_mfma_f32_16x16x32_bf16 v[166:169], v[130:133], v[70:73], v[166:169]
	v_cvt_pk_bf16_f32 v88, v94, v95
	v_cvt_pk_bf16_f32 v89, v96, v97
	s_waitcnt lgkmcnt(5)
	v_mfma_f32_32x32x16_bf16 v[66:81], v[238:241], v[134:137], 0
	v_exp_f32_e32 v98, v98
	v_exp_f32_e32 v99, v99
	v_exp_f32_e32 v100, v100
	ds_read_b128 v[238:241], v250 offset:9280
	v_mfma_f32_32x32x16_bf16 v[34:49], v[182:185], v[86:89], v[34:49]
	v_exp_f32_e32 v101, v101
	v_exp_f32_e32 v102, v102
	v_exp_f32_e32 v103, v103
	ds_read_b64_tr_b16 v[182:183], v252 offset:9216
	ds_read_b64_tr_b16 v[184:185], v252 offset:10752
	v_mfma_f32_32x32x16_bf16 v[50:65], v[186:189], v[86:89], v[50:65]
	v_exp_f32_e32 v104, v104
	v_exp_f32_e32 v105, v105
	v_cvt_pk_bf16_f32 v98, v98, v99
	v_cvt_pk_bf16_f32 v99, v100, v101
	ds_read_b64_tr_b16 v[186:187], v252 offset:9280
	ds_read_b64_tr_b16 v[188:189], v252 offset:10816
	v_mfma_f32_16x16x32_bf16 v[170:173], v[130:133], v[86:89], v[170:173]
	v_cvt_pk_bf16_f32 v100, v102, v103
	v_cvt_pk_bf16_f32 v101, v104, v105
	s_waitcnt lgkmcnt(5)
	v_mfma_f32_32x32x16_bf16 v[66:81], v[242:245], v[138:141], v[66:81]
	v_exp_f32_e32 v114, v114
	v_exp_f32_e32 v115, v115
	v_exp_f32_e32 v116, v116
	ds_read_b128 v[242:245], v250 offset:9312
	v_mfma_f32_32x32x16_bf16 v[2:17], v[174:177], v[98:101], v[2:17]
	v_exp_f32_e32 v117, v117
	v_exp_f32_e32 v118, v118
	v_exp_f32_e32 v119, v119
	v_mfma_f32_32x32x16_bf16 v[18:33], v[178:181], v[98:101], v[18:33]
	v_exp_f32_e32 v120, v120
	v_exp_f32_e32 v121, v121
	v_cvt_pk_bf16_f32 v114, v114, v115
	v_cvt_pk_bf16_f32 v115, v116, v117
	v_mfma_f32_16x16x32_bf16 v[166:169], v[130:133], v[98:101], v[166:169]
	v_cvt_pk_bf16_f32 v116, v118, v119
	v_cvt_pk_bf16_f32 v117, v120, v121
	s_waitcnt lgkmcnt(5)
	v_mfma_f32_32x32x16_bf16 v[82:97], v[238:241], v[142:145], 0
	v_exp_f32_e32 v106, v106
	v_exp_f32_e32 v107, v107
	v_exp_f32_e32 v108, v108
	ds_read_b128 v[238:241], v250 offset:13824
	v_mfma_f32_32x32x16_bf16 v[34:49], v[174:177], v[114:117], v[34:49]
	v_exp_f32_e32 v109, v109
	v_exp_f32_e32 v110, v110
	v_exp_f32_e32 v111, v111
	ds_read_b64_tr_b16 v[174:175], v252 offset:12288
	ds_read_b64_tr_b16 v[176:177], v252 offset:13824
	v_mfma_f32_32x32x16_bf16 v[50:65], v[178:181], v[114:117], v[50:65]
	v_exp_f32_e32 v112, v112
	v_exp_f32_e32 v113, v113
	v_cvt_pk_bf16_f32 v102, v106, v107
	v_cvt_pk_bf16_f32 v103, v108, v109
	ds_read_b64_tr_b16 v[178:179], v252 offset:12352
	ds_read_b64_tr_b16 v[180:181], v252 offset:13888
	v_mfma_f32_16x16x32_bf16 v[170:173], v[130:133], v[114:117], v[170:173]
	v_cvt_pk_bf16_f32 v104, v110, v111
	v_cvt_pk_bf16_f32 v105, v112, v113
	s_waitcnt lgkmcnt(5)
	v_mfma_f32_32x32x16_bf16 v[82:97], v[242:245], v[146:149], v[82:97]
	v_exp_f32_e32 v122, v122
	v_exp_f32_e32 v123, v123
	v_exp_f32_e32 v124, v124
	ds_read_b128 v[242:245], v250 offset:13856
	v_mfma_f32_32x32x16_bf16 v[2:17], v[182:185], v[102:105], v[2:17]
	v_exp_f32_e32 v125, v125
	v_exp_f32_e32 v126, v126
	v_exp_f32_e32 v127, v127
	v_mfma_f32_32x32x16_bf16 v[18:33], v[186:189], v[102:105], v[18:33]
	v_exp_f32_e32 v128, v128
	v_exp_f32_e32 v129, v129
	v_cvt_pk_bf16_f32 v118, v122, v123
	v_cvt_pk_bf16_f32 v119, v124, v125
	v_mfma_f32_16x16x32_bf16 v[166:169], v[130:133], v[102:105], v[166:169]
	v_cvt_pk_bf16_f32 v120, v126, v127
	v_cvt_pk_bf16_f32 v121, v128, v129
	s_waitcnt lgkmcnt(5)
	v_mfma_f32_32x32x16_bf16 v[98:113], v[238:241], v[134:137], 0
	v_exp_f32_e32 v66, v66
	v_exp_f32_e32 v67, v67
	v_exp_f32_e32 v68, v68
	ds_read_b128 v[238:241], v250 offset:13888
	v_mfma_f32_32x32x16_bf16 v[34:49], v[182:185], v[118:121], v[34:49]
	v_exp_f32_e32 v69, v69
	v_exp_f32_e32 v70, v70
	v_exp_f32_e32 v71, v71
	ds_read_b64_tr_b16 v[182:183], v252 offset:15360
	ds_read_b64_tr_b16 v[184:185], v252 offset:16896
	v_mfma_f32_32x32x16_bf16 v[50:65], v[186:189], v[118:121], v[50:65]
	v_exp_f32_e32 v72, v72
	v_exp_f32_e32 v73, v73
	v_cvt_pk_bf16_f32 v66, v66, v67
	v_cvt_pk_bf16_f32 v67, v68, v69
	ds_read_b64_tr_b16 v[186:187], v252 offset:15424
	ds_read_b64_tr_b16 v[188:189], v252 offset:16960
	v_mfma_f32_16x16x32_bf16 v[170:173], v[130:133], v[118:121], v[170:173]
	v_cvt_pk_bf16_f32 v68, v70, v71
	v_cvt_pk_bf16_f32 v69, v72, v73
	s_waitcnt lgkmcnt(5)
	v_mfma_f32_32x32x16_bf16 v[98:113], v[242:245], v[138:141], v[98:113]
	v_exp_f32_e32 v82, v82
	v_exp_f32_e32 v83, v83
	v_exp_f32_e32 v84, v84
	ds_read_b128 v[242:245], v250 offset:13920
	v_mfma_f32_32x32x16_bf16 v[2:17], v[174:177], v[66:69], v[2:17]
	v_exp_f32_e32 v85, v85
	v_exp_f32_e32 v86, v86
	v_exp_f32_e32 v87, v87
	v_mfma_f32_32x32x16_bf16 v[18:33], v[178:181], v[66:69], v[18:33]
	v_exp_f32_e32 v88, v88
	v_exp_f32_e32 v89, v89
	v_cvt_pk_bf16_f32 v82, v82, v83
	v_cvt_pk_bf16_f32 v83, v84, v85
	v_mfma_f32_16x16x32_bf16 v[166:169], v[130:133], v[66:69], v[166:169]
	v_cvt_pk_bf16_f32 v84, v86, v87
	v_cvt_pk_bf16_f32 v85, v88, v89
	s_barrier
	s_waitcnt lgkmcnt(5)
	v_mfma_f32_32x32x16_bf16 v[114:129], v[238:241], v[142:145], 0
	v_exp_f32_e32 v74, v74
	v_exp_f32_e32 v75, v75
	v_exp_f32_e32 v76, v76
	ds_read_b128 v[238:241], v251
	v_mfma_f32_32x32x16_bf16 v[34:49], v[174:177], v[82:85], v[34:49]
	v_exp_f32_e32 v77, v77
	v_exp_f32_e32 v78, v78
	v_exp_f32_e32 v79, v79
	ds_read_b64_tr_b16 v[174:175], v252 offset:18432
	ds_read_b64_tr_b16 v[176:177], v252 offset:19968
	v_mfma_f32_32x32x16_bf16 v[50:65], v[178:181], v[82:85], v[50:65]
	v_exp_f32_e32 v80, v80
	v_exp_f32_e32 v81, v81
	v_cvt_pk_bf16_f32 v70, v74, v75
	v_cvt_pk_bf16_f32 v71, v76, v77
	ds_read_b64_tr_b16 v[178:179], v252 offset:18496
	ds_read_b64_tr_b16 v[180:181], v252 offset:20032
	v_mfma_f32_16x16x32_bf16 v[170:173], v[130:133], v[82:85], v[170:173]
	v_cvt_pk_bf16_f32 v72, v78, v79
	v_cvt_pk_bf16_f32 v73, v80, v81
	s_waitcnt lgkmcnt(5)
	v_mfma_f32_32x32x16_bf16 v[114:129], v[242:245], v[146:149], v[114:129]
	v_exp_f32_e32 v90, v90
	v_exp_f32_e32 v91, v91
	v_exp_f32_e32 v92, v92
	ds_read_b128 v[242:245], v251 offset:32
	v_mfma_f32_32x32x16_bf16 v[2:17], v[182:185], v[70:73], v[2:17]
	v_exp_f32_e32 v93, v93
	v_exp_f32_e32 v94, v94
	v_exp_f32_e32 v95, v95
	v_mfma_f32_32x32x16_bf16 v[18:33], v[186:189], v[70:73], v[18:33]
	v_exp_f32_e32 v96, v96
	v_exp_f32_e32 v97, v97
	v_cvt_pk_bf16_f32 v86, v90, v91
	v_cvt_pk_bf16_f32 v87, v92, v93
	v_mfma_f32_16x16x32_bf16 v[166:169], v[130:133], v[70:73], v[166:169]
	v_cvt_pk_bf16_f32 v88, v94, v95
	v_cvt_pk_bf16_f32 v89, v96, v97
	s_waitcnt lgkmcnt(5)
	v_mfma_f32_32x32x16_bf16 v[66:81], v[238:241], v[134:137], 0
	v_exp_f32_e32 v98, v98
	v_exp_f32_e32 v99, v99
	v_exp_f32_e32 v100, v100
	ds_read_b128 v[238:241], v251 offset:64
	v_mfma_f32_32x32x16_bf16 v[34:49], v[182:185], v[86:89], v[34:49]
	v_exp_f32_e32 v101, v101
	v_exp_f32_e32 v102, v102
	v_exp_f32_e32 v103, v103
	ds_read_b64_tr_b16 v[182:183], v252 offset:21504
	ds_read_b64_tr_b16 v[184:185], v252 offset:23040
	v_mfma_f32_32x32x16_bf16 v[50:65], v[186:189], v[86:89], v[50:65]
	v_exp_f32_e32 v104, v104
	v_exp_f32_e32 v105, v105
	v_cvt_pk_bf16_f32 v98, v98, v99
	v_cvt_pk_bf16_f32 v99, v100, v101
	ds_read_b64_tr_b16 v[186:187], v252 offset:21568
	ds_read_b64_tr_b16 v[188:189], v252 offset:23104
	v_mfma_f32_16x16x32_bf16 v[170:173], v[130:133], v[86:89], v[170:173]
	v_cvt_pk_bf16_f32 v100, v102, v103
	v_cvt_pk_bf16_f32 v101, v104, v105
	s_waitcnt lgkmcnt(5)
	v_mfma_f32_32x32x16_bf16 v[66:81], v[242:245], v[138:141], v[66:81]
	v_exp_f32_e32 v114, v114
	v_exp_f32_e32 v115, v115
	v_exp_f32_e32 v116, v116
	ds_read_b128 v[242:245], v251 offset:96
	v_mfma_f32_32x32x16_bf16 v[2:17], v[174:177], v[98:101], v[2:17]
	v_exp_f32_e32 v117, v117
	v_exp_f32_e32 v118, v118
	v_exp_f32_e32 v119, v119
	v_mfma_f32_32x32x16_bf16 v[18:33], v[178:181], v[98:101], v[18:33]
	v_exp_f32_e32 v120, v120
	v_exp_f32_e32 v121, v121
	v_cvt_pk_bf16_f32 v114, v114, v115
	v_cvt_pk_bf16_f32 v115, v116, v117
	v_mfma_f32_16x16x32_bf16 v[166:169], v[130:133], v[98:101], v[166:169]
	v_cvt_pk_bf16_f32 v116, v118, v119
	v_cvt_pk_bf16_f32 v117, v120, v121
	s_waitcnt lgkmcnt(5)
	v_mfma_f32_32x32x16_bf16 v[82:97], v[238:241], v[142:145], 0
	v_exp_f32_e32 v106, v106
	v_exp_f32_e32 v107, v107
	v_exp_f32_e32 v108, v108
	ds_read_b128 v[238:241], v251 offset:4608
	v_mfma_f32_32x32x16_bf16 v[34:49], v[174:177], v[114:117], v[34:49]
	v_exp_f32_e32 v109, v109
	v_exp_f32_e32 v110, v110
	v_exp_f32_e32 v111, v111
	ds_read_b64_tr_b16 v[174:175], v215
	ds_read_b64_tr_b16 v[176:177], v215 offset:1536
	v_mfma_f32_32x32x16_bf16 v[50:65], v[178:181], v[114:117], v[50:65]
	v_exp_f32_e32 v112, v112
	v_exp_f32_e32 v113, v113
	v_cvt_pk_bf16_f32 v102, v106, v107
	v_cvt_pk_bf16_f32 v103, v108, v109
	ds_read_b64_tr_b16 v[178:179], v215 offset:64
	ds_read_b64_tr_b16 v[180:181], v215 offset:1600
	v_mfma_f32_16x16x32_bf16 v[170:173], v[130:133], v[114:117], v[170:173]
	v_cvt_pk_bf16_f32 v104, v110, v111
	v_cvt_pk_bf16_f32 v105, v112, v113
	s_waitcnt lgkmcnt(5)
	v_mfma_f32_32x32x16_bf16 v[82:97], v[242:245], v[146:149], v[82:97]
	v_exp_f32_e32 v122, v122
	v_exp_f32_e32 v123, v123
	v_exp_f32_e32 v124, v124
	ds_read_b128 v[242:245], v251 offset:4640
	v_mfma_f32_32x32x16_bf16 v[2:17], v[182:185], v[102:105], v[2:17]
	v_exp_f32_e32 v125, v125
	v_exp_f32_e32 v126, v126
	v_exp_f32_e32 v127, v127
	v_mfma_f32_32x32x16_bf16 v[18:33], v[186:189], v[102:105], v[18:33]
	v_exp_f32_e32 v128, v128
	v_exp_f32_e32 v129, v129
	v_cvt_pk_bf16_f32 v118, v122, v123
	v_cvt_pk_bf16_f32 v119, v124, v125
	v_mfma_f32_16x16x32_bf16 v[166:169], v[130:133], v[102:105], v[166:169]
	v_cvt_pk_bf16_f32 v120, v126, v127
	v_cvt_pk_bf16_f32 v121, v128, v129
	s_cmp_lg_u32 s14, s10
	s_cbranch_scc1 .Latt_loop
	s_waitcnt lgkmcnt(0)
	s_nop 1
	v_mfma_f32_16x16x32_bf16 v[170:173], v[130:133], v[118:121], v[170:173]
	v_mfma_f32_32x32x16_bf16 v[34:49], v[182:185], v[118:121], v[34:49]
	v_mfma_f32_32x32x16_bf16 v[50:65], v[186:189], v[118:121], v[50:65]
	s_nop 11
	global_load_dwordx4 v[98:101], v[212:213], off offset:32
	global_load_dwordx4 v[102:105], v[212:213], off offset:64
	global_load_dwordx4 v[106:109], v[212:213], off offset:96
	global_load_dwordx4 v[110:113], v[212:213], off offset:128
	global_load_dwordx4 v[114:117], v[212:213], off offset:160
	global_load_dwordx4 v[122:125], v[212:213], off offset:192
	global_load_dwordx4 v[126:129], v[212:213], off offset:224
	ds_bpermute_b32 v66, v237, v166
	s_nop 3
	ds_bpermute_b32 v67, v237, v170
	s_lshl_b32 s64, s9, 1
	v_mov_b32_e32 v215, v191
	s_mov_b32 s2, 0xf226000
	s_waitcnt lgkmcnt(1)
	v_div_scale_f32 v68, s[10:11], v66, v66, 1.0
	v_rcp_f32_e32 v69, v68
	s_add_i32 s8, s8, 1
	s_cmp_eq_u32 s8, s7
	v_fma_f32 v70, -v68, v69, 1.0
	v_fmac_f32_e32 v69, v70, v69
	v_div_scale_f32 v70, vcc, 1.0, v66, 1.0
	v_mul_f32_e32 v71, v70, v69
	v_fma_f32 v72, -v68, v71, v70
	v_fmac_f32_e32 v71, v72, v69
	v_fma_f32 v68, -v68, v71, v70
	v_div_fmas_f32 v68, v68, v69, v71
	v_div_fixup_f32 v66, v68, v66, 1.0
	s_waitcnt lgkmcnt(0)
	v_div_scale_f32 v68, s[10:11], v67, v67, v230
	v_rcp_f32_e32 v69, v68
	s_mov_b64 s[10:11], 0xf226400
	v_fma_f32 v70, -v68, v69, 1.0
	v_fmac_f32_e32 v69, v70, v69
	v_div_scale_f32 v70, vcc, v230, v67, v230
	v_mul_f32_e32 v71, v70, v69
	v_fma_f32 v72, -v68, v71, v70
	v_fmac_f32_e32 v71, v72, v69
	v_fma_f32 v68, -v68, v71, v70
	v_div_fmas_f32 v68, v68, v69, v71
	v_div_fixup_f32 v68, v68, v67, v230
	v_pk_mul_f32 v[62:63], v[62:63], v[68:69] op_sel_hi:[1,0]
	v_pk_mul_f32 v[34:35], v[34:35], v[68:69] op_sel_hi:[1,0]
	v_pk_fma_f32 v[30:31], v[30:31], v[66:67], v[62:63] op_sel_hi:[1,0,1] neg_lo:[0,0,1] neg_hi:[0,0,1]
	v_pk_mul_f32 v[62:63], v[64:65], v[68:69] op_sel_hi:[1,0]
	v_pk_mul_f32 v[36:37], v[36:37], v[68:69] op_sel_hi:[1,0]
	v_pk_fma_f32 v[32:33], v[32:33], v[66:67], v[62:63] op_sel_hi:[1,0,1] neg_lo:[0,0,1] neg_hi:[0,0,1]
	v_lshlrev_b64 v[62:63], 11, v[216:217]
	v_lshl_add_u64 v[62:63], s[54:55], 0, v[62:63]
	v_lshl_add_u64 v[74:75], v[62:63], 0, s[64:65]
	global_load_dwordx4 v[62:65], v[212:213], off
	v_pk_fma_f32 v[34:35], v[2:3], v[66:67], v[34:35] op_sel_hi:[1,0,1] neg_lo:[0,0,1] neg_hi:[0,0,1]
	v_pk_fma_f32 v[4:5], v[4:5], v[66:67], v[36:37] op_sel_hi:[1,0,1] neg_lo:[0,0,1] neg_hi:[0,0,1]
	v_pk_mul_f32 v[76:77], v[34:35], v[34:35]
	v_pk_mul_f32 v[40:41], v[40:41], v[68:69] op_sel_hi:[1,0]
	v_pk_mul_f32 v[38:39], v[38:39], v[68:69] op_sel_hi:[1,0]
	v_pk_mul_f32 v[44:45], v[44:45], v[68:69] op_sel_hi:[1,0]
	v_pk_mul_f32 v[42:43], v[42:43], v[68:69] op_sel_hi:[1,0]
	v_pk_mul_f32 v[48:49], v[48:49], v[68:69] op_sel_hi:[1,0]
	v_pk_mul_f32 v[46:47], v[46:47], v[68:69] op_sel_hi:[1,0]
	v_pk_mul_f32 v[52:53], v[52:53], v[68:69] op_sel_hi:[1,0]
	v_pk_mul_f32 v[50:51], v[50:51], v[68:69] op_sel_hi:[1,0]
	v_pk_mul_f32 v[56:57], v[56:57], v[68:69] op_sel_hi:[1,0]
	v_pk_mul_f32 v[54:55], v[54:55], v[68:69] op_sel_hi:[1,0]
	v_pk_mul_f32 v[60:61], v[60:61], v[68:69] op_sel_hi:[1,0]
	v_pk_mul_f32 v[58:59], v[58:59], v[68:69] op_sel_hi:[1,0]
	v_pk_mul_f32 v[36:37], v[4:5], v[4:5]
	v_pk_fma_f32 v[8:9], v[8:9], v[66:67], v[40:41] op_sel_hi:[1,0,1] neg_lo:[0,0,1] neg_hi:[0,0,1]
	v_pk_fma_f32 v[38:39], v[6:7], v[66:67], v[38:39] op_sel_hi:[1,0,1] neg_lo:[0,0,1] neg_hi:[0,0,1]
	v_pk_fma_f32 v[12:13], v[12:13], v[66:67], v[44:45] op_sel_hi:[1,0,1] neg_lo:[0,0,1] neg_hi:[0,0,1]
	v_pk_fma_f32 v[10:11], v[10:11], v[66:67], v[42:43] op_sel_hi:[1,0,1] neg_lo:[0,0,1] neg_hi:[0,0,1]
	v_pk_fma_f32 v[16:17], v[16:17], v[66:67], v[48:49] op_sel_hi:[1,0,1] neg_lo:[0,0,1] neg_hi:[0,0,1]
	v_pk_fma_f32 v[14:15], v[14:15], v[66:67], v[46:47] op_sel_hi:[1,0,1] neg_lo:[0,0,1] neg_hi:[0,0,1]
	v_pk_fma_f32 v[20:21], v[20:21], v[66:67], v[52:53] op_sel_hi:[1,0,1] neg_lo:[0,0,1] neg_hi:[0,0,1]
	v_pk_fma_f32 v[18:19], v[18:19], v[66:67], v[50:51] op_sel_hi:[1,0,1] neg_lo:[0,0,1] neg_hi:[0,0,1]
	v_pk_fma_f32 v[24:25], v[24:25], v[66:67], v[56:57] op_sel_hi:[1,0,1] neg_lo:[0,0,1] neg_hi:[0,0,1]
	v_pk_fma_f32 v[22:23], v[22:23], v[66:67], v[54:55] op_sel_hi:[1,0,1] neg_lo:[0,0,1] neg_hi:[0,0,1]
	v_pk_fma_f32 v[28:29], v[28:29], v[66:67], v[60:61] op_sel_hi:[1,0,1] neg_lo:[0,0,1] neg_hi:[0,0,1]
	v_pk_fma_f32 v[26:27], v[26:27], v[66:67], v[58:59] op_sel_hi:[1,0,1] neg_lo:[0,0,1] neg_hi:[0,0,1]
	v_add_f32_e32 v66, v76, v77
	v_add_f32_e32 v36, v36, v66
	v_pk_mul_f32 v[6:7], v[38:39], v[38:39]
	v_add_f32_e32 v36, v37, v36
	v_add_f32_e32 v6, v6, v36
	v_pk_mul_f32 v[40:41], v[8:9], v[8:9]
	v_add_f32_e32 v6, v7, v6
	v_add_f32_e32 v6, v40, v6
	v_pk_mul_f32 v[42:43], v[10:11], v[10:11]
	v_add_f32_e32 v6, v41, v6
	v_add_f32_e32 v6, v42, v6
	v_pk_mul_f32 v[44:45], v[12:13], v[12:13]
	v_add_f32_e32 v6, v43, v6
	v_add_f32_e32 v6, v44, v6
	v_pk_mul_f32 v[46:47], v[14:15], v[14:15]
	v_add_f32_e32 v6, v45, v6
	v_add_f32_e32 v6, v46, v6
	v_pk_mul_f32 v[48:49], v[16:17], v[16:17]
	v_add_f32_e32 v6, v47, v6
	v_add_f32_e32 v6, v48, v6
	v_pk_mul_f32 v[50:51], v[18:19], v[18:19]
	v_add_f32_e32 v6, v49, v6
	v_add_f32_e32 v6, v50, v6
	v_pk_mul_f32 v[52:53], v[20:21], v[20:21]
	v_add_f32_e32 v6, v51, v6
	v_add_f32_e32 v6, v52, v6
	v_pk_mul_f32 v[54:55], v[22:23], v[22:23]
	v_add_f32_e32 v6, v53, v6
	v_add_f32_e32 v6, v54, v6
	v_pk_mul_f32 v[56:57], v[24:25], v[24:25]
	v_add_f32_e32 v6, v55, v6
	v_add_f32_e32 v6, v56, v6
	v_pk_mul_f32 v[58:59], v[26:27], v[26:27]
	v_add_f32_e32 v6, v57, v6
	v_add_f32_e32 v6, v58, v6
	v_pk_mul_f32 v[60:61], v[28:29], v[28:29]
	v_add_f32_e32 v6, v59, v6
	v_add_f32_e32 v6, v60, v6
	v_pk_mul_f32 v[70:71], v[30:31], v[30:31]
	v_add_f32_e32 v6, v61, v6
	v_add_f32_e32 v6, v70, v6
	v_pk_mul_f32 v[72:73], v[32:33], v[32:33]
	v_add_f32_e32 v6, v71, v6
	v_add_f32_e32 v6, v72, v6
	v_add_f32_e32 v6, v73, v6
	ds_bpermute_b32 v7, v229, v6
	v_lshl_add_u64 v[74:75], v[74:75], 0, v[214:215]
	v_lshl_add_u64 v[2:3], v[74:75], 0, s[10:11]
	s_waitcnt lgkmcnt(0)
	v_add_f32_e32 v6, v6, v7
	v_fmamk_f32 v6, v6, 0x3c800000, v192
	v_cmp_gt_f32_e32 vcc, s70, v6
	v_mul_f32_e32 v7, 0x4b800000, v6
	s_nop 0
	v_cndmask_b32_e32 v6, v6, v7, vcc
	v_rsq_f32_e32 v6, v6
	s_nop 0
	v_mul_f32_e32 v7, 0x45800000, v6
	v_cndmask_b32_e32 v6, v6, v7, vcc
	v_mul_f32_e32 v36, v233, v6
	v_pk_mul_f32 v[6:7], v[34:35], v[36:37] op_sel_hi:[1,0]
	v_pk_mul_f32 v[4:5], v[4:5], v[36:37] op_sel_hi:[1,0]
	s_waitcnt vmcnt(0)
	v_pk_mul_f32 v[6:7], v[62:63], v[6:7]
	v_pk_mul_f32 v[4:5], v[64:65], v[4:5]
	v_cvt_pk_bf16_f32 v6, v6, v7
	v_cvt_pk_bf16_f32 v7, v4, v5
	v_add_co_u32_e32 v4, vcc, s2, v74
	v_pk_mul_f32 v[34:35], v[38:39], v[36:37] op_sel_hi:[1,0]
	s_nop 0
	v_addc_co_u32_e32 v5, vcc, 0, v75, vcc
	global_store_dwordx2 v[4:5], v[6:7], off offset:1024
	v_pk_mul_f32 v[8:9], v[8:9], v[36:37] op_sel_hi:[1,0]
	v_mov_b64_e32 v[4:5], v[98:99]
	v_mov_b64_e32 v[6:7], v[100:101]
	v_pk_mul_f32 v[4:5], v[4:5], v[34:35]
	v_pk_mul_f32 v[6:7], v[6:7], v[8:9]
	v_cvt_pk_bf16_f32 v4, v4, v5
	v_cvt_pk_bf16_f32 v5, v6, v7
	global_store_dwordx2 v[2:3], v[4:5], off offset:16
	v_pk_mul_f32 v[8:9], v[10:11], v[36:37] op_sel_hi:[1,0]
	v_mov_b64_e32 v[4:5], v[102:103]
	v_mov_b64_e32 v[6:7], v[104:105]
	v_pk_mul_f32 v[4:5], v[4:5], v[8:9]
	v_pk_mul_f32 v[8:9], v[12:13], v[36:37] op_sel_hi:[1,0]
	v_cvt_pk_bf16_f32 v4, v4, v5
	v_pk_mul_f32 v[6:7], v[6:7], v[8:9]
	v_pk_mul_f32 v[8:9], v[14:15], v[36:37] op_sel_hi:[1,0]
	v_cvt_pk_bf16_f32 v5, v6, v7
	global_store_dwordx2 v[2:3], v[4:5], off offset:32
	v_mov_b64_e32 v[4:5], v[106:107]
	v_mov_b64_e32 v[6:7], v[108:109]
	v_pk_mul_f32 v[4:5], v[4:5], v[8:9]
	v_pk_mul_f32 v[8:9], v[16:17], v[36:37] op_sel_hi:[1,0]
	v_cvt_pk_bf16_f32 v4, v4, v5
	v_pk_mul_f32 v[6:7], v[6:7], v[8:9]
	v_pk_mul_f32 v[8:9], v[18:19], v[36:37] op_sel_hi:[1,0]
	v_cvt_pk_bf16_f32 v5, v6, v7
	global_store_dwordx2 v[2:3], v[4:5], off offset:48
	v_mov_b64_e32 v[4:5], v[110:111]
	v_mov_b64_e32 v[6:7], v[112:113]
	v_pk_mul_f32 v[4:5], v[4:5], v[8:9]
	v_pk_mul_f32 v[8:9], v[20:21], v[36:37] op_sel_hi:[1,0]
	v_cvt_pk_bf16_f32 v4, v4, v5
	v_pk_mul_f32 v[6:7], v[6:7], v[8:9]
	v_pk_mul_f32 v[8:9], v[22:23], v[36:37] op_sel_hi:[1,0]
	v_cvt_pk_bf16_f32 v5, v6, v7
	global_store_dwordx2 v[2:3], v[4:5], off offset:64
	v_mov_b64_e32 v[4:5], v[114:115]
	v_mov_b64_e32 v[6:7], v[116:117]
	v_pk_mul_f32 v[4:5], v[4:5], v[8:9]
	v_pk_mul_f32 v[8:9], v[24:25], v[36:37] op_sel_hi:[1,0]
	v_cvt_pk_bf16_f32 v4, v4, v5
	v_pk_mul_f32 v[6:7], v[6:7], v[8:9]
	v_pk_mul_f32 v[8:9], v[26:27], v[36:37] op_sel_hi:[1,0]
	v_cvt_pk_bf16_f32 v5, v6, v7
	global_store_dwordx2 v[2:3], v[4:5], off offset:80
	v_mov_b64_e32 v[4:5], v[122:123]
	v_mov_b64_e32 v[6:7], v[124:125]
	v_pk_mul_f32 v[4:5], v[4:5], v[8:9]
	v_pk_mul_f32 v[8:9], v[28:29], v[36:37] op_sel_hi:[1,0]
	v_cvt_pk_bf16_f32 v4, v4, v5
	v_pk_mul_f32 v[6:7], v[6:7], v[8:9]
	v_pk_mul_f32 v[8:9], v[30:31], v[36:37] op_sel_hi:[1,0]
	v_cvt_pk_bf16_f32 v5, v6, v7
	global_store_dwordx2 v[2:3], v[4:5], off offset:96
	v_mov_b64_e32 v[4:5], v[126:127]
	v_mov_b64_e32 v[6:7], v[128:129]
	v_pk_mul_f32 v[4:5], v[4:5], v[8:9]
	v_pk_mul_f32 v[8:9], v[32:33], v[36:37] op_sel_hi:[1,0]
	v_cvt_pk_bf16_f32 v4, v4, v5
	v_pk_mul_f32 v[6:7], v[6:7], v[8:9]
	s_nop 0
	v_cvt_pk_bf16_f32 v5, v6, v7
	global_store_dwordx2 v[2:3], v[4:5], off offset:112
	s_cbranch_scc0 .LBB0_745
